# attention unit epilogue (guide 7.3): v_permlane32_swap pairs, four 16-byte stores instead of eight 8-byte stores per lane
# speedup vs baseline: 1.0174x; 1.0174x over previous
.LBB0_1053:
	ds_bpermute_b32 v0, v146, v148
	s_lshl_b32 s68, s17, 7
	v_lshlrev_b32_e32 v10, 3, v132
	v_mov_b32_e32 v11, v4
	s_waitcnt lgkmcnt(0)
	v_add_f32_e32 v0, v148, v0
	v_div_scale_f32 v1, s[0:1], v0, v0, 1.0
	v_rcp_f32_e32 v2, v1
	s_add_i32 s0, s19, s18
	v_fma_f32 v3, -v1, v2, 1.0
	v_fmac_f32_e32 v2, v3, v2
	v_div_scale_f32 v3, vcc, 1.0, v0, 1.0
	v_mul_f32_e32 v5, v3, v2
	v_fma_f32 v6, -v1, v5, v3
	v_fmac_f32_e32 v5, v6, v2
	v_fma_f32 v1, -v1, v5, v3
	v_div_fmas_f32 v1, v1, v2, v5
	v_add_u32_e32 v2, s0, v133
	v_ashrrev_i32_e32 v3, 31, v2
	v_mov_b64_e32 v[6:7], s[26:27]
	v_mad_i64_i32 v[8:9], s[0:1], v2, s92, v[6:7]
	v_lshlrev_b64 v[2:3], 9, v[2:3]
	v_sub_co_u32_e32 v2, vcc, 0, v2
	v_lshl_add_u64 v[6:7], v[8:9], 0, s[68:69]
	s_nop 0
	v_subb_co_u32_e32 v3, vcc, 0, v3, vcc
	v_lshl_add_u64 v[2:3], v[8:9], 0, v[2:3]
	v_lshl_add_u64 v[12:13], v[6:7], 0, v[10:11]
	s_mov_b64 s[0:1], 0x4512600
	v_lshl_add_u64 v[2:3], v[2:3], 0, s[68:69]
	v_lshl_add_u64 v[6:7], v[12:13], 0, s[0:1]
	v_lshl_add_u64 v[8:9], v[2:3], 0, v[10:11]
	s_mov_b64 s[0:1], 0x6d12400
	v_lshl_add_u64 v[2:3], v[8:9], 0, s[0:1]
	v_div_fixup_f32 v0, v1, v0, 1.0
	global_load_dwordx2 v[150:151], v[6:7], off
	global_load_dwordx2 v[152:153], v[6:7], off offset:16
	global_load_dwordx2 v[154:155], v[6:7], off offset:32
	global_load_dwordx2 v[156:157], v[6:7], off offset:48
	global_load_dwordx2 v[158:159], v[6:7], off offset:64
	global_load_dwordx2 v[160:161], v[6:7], off offset:80
	global_load_dwordx2 v[162:163], v[6:7], off offset:96
	global_load_dwordx2 v[164:165], v[6:7], off offset:112
	v_lshlrev_b32_e32 v10, 3, v132
	v_mov_b32_e32 v11, v4
	v_lshl_add_u64 v[2:3], v[2:3], 0, v[10:11]
	s_waitcnt vmcnt(7)
	v_pk_mul_f32 v[12:13], v[32:33], v[0:1] op_sel_hi:[1,0]
	v_lshlrev_b32_e32 v14, 16, v150
	v_and_b32_e32 v15, 0xffff0000, v150
	v_pk_mul_f32 v[12:13], v[12:13], v[14:15]
	v_pk_mul_f32 v[8:9], v[34:35], v[0:1] op_sel_hi:[1,0]
	v_cvt_pk_bf16_f32 v166, v12, v13
	v_lshlrev_b32_e32 v14, 16, v151
	v_and_b32_e32 v15, 0xffff0000, v151
	v_pk_mul_f32 v[8:9], v[8:9], v[14:15]
	s_nop 0
	v_cvt_pk_bf16_f32 v167, v8, v9
	s_waitcnt vmcnt(6)
	v_pk_mul_f32 v[12:13], v[36:37], v[0:1] op_sel_hi:[1,0]
	v_lshlrev_b32_e32 v14, 16, v152
	v_and_b32_e32 v15, 0xffff0000, v152
	v_pk_mul_f32 v[12:13], v[12:13], v[14:15]
	v_pk_mul_f32 v[8:9], v[38:39], v[0:1] op_sel_hi:[1,0]
	v_cvt_pk_bf16_f32 v168, v12, v13
	v_lshlrev_b32_e32 v14, 16, v153
	v_and_b32_e32 v15, 0xffff0000, v153
	v_pk_mul_f32 v[8:9], v[8:9], v[14:15]
	s_nop 0
	v_cvt_pk_bf16_f32 v169, v8, v9
	s_nop 1
	v_permlane32_swap_b32_e32 v166, v168
	v_permlane32_swap_b32_e32 v167, v169
	global_store_dwordx4 v[2:3], v[166:169], off
	s_waitcnt vmcnt(6)
	v_pk_mul_f32 v[12:13], v[40:41], v[0:1] op_sel_hi:[1,0]
	v_lshlrev_b32_e32 v14, 16, v154
	v_and_b32_e32 v15, 0xffff0000, v154
	v_pk_mul_f32 v[12:13], v[12:13], v[14:15]
	v_pk_mul_f32 v[8:9], v[42:43], v[0:1] op_sel_hi:[1,0]
	v_cvt_pk_bf16_f32 v170, v12, v13
	v_lshlrev_b32_e32 v14, 16, v155
	v_and_b32_e32 v15, 0xffff0000, v155
	v_pk_mul_f32 v[8:9], v[8:9], v[14:15]
	s_nop 0
	v_cvt_pk_bf16_f32 v171, v8, v9
	s_waitcnt vmcnt(5)
	v_pk_mul_f32 v[12:13], v[44:45], v[0:1] op_sel_hi:[1,0]
	v_lshlrev_b32_e32 v14, 16, v156
	v_and_b32_e32 v15, 0xffff0000, v156
	v_pk_mul_f32 v[12:13], v[12:13], v[14:15]
	v_pk_mul_f32 v[8:9], v[46:47], v[0:1] op_sel_hi:[1,0]
	v_cvt_pk_bf16_f32 v172, v12, v13
	v_lshlrev_b32_e32 v14, 16, v157
	v_and_b32_e32 v15, 0xffff0000, v157
	v_pk_mul_f32 v[8:9], v[8:9], v[14:15]
	s_nop 0
	v_cvt_pk_bf16_f32 v173, v8, v9
	s_nop 1
	v_permlane32_swap_b32_e32 v170, v172
	v_permlane32_swap_b32_e32 v171, v173
	global_store_dwordx4 v[2:3], v[170:173], off offset:32
	s_waitcnt vmcnt(5)
	v_pk_mul_f32 v[12:13], v[16:17], v[0:1] op_sel_hi:[1,0]
	v_lshlrev_b32_e32 v14, 16, v158
	v_and_b32_e32 v15, 0xffff0000, v158
	v_pk_mul_f32 v[12:13], v[12:13], v[14:15]
	v_pk_mul_f32 v[8:9], v[18:19], v[0:1] op_sel_hi:[1,0]
	v_cvt_pk_bf16_f32 v174, v12, v13
	v_lshlrev_b32_e32 v14, 16, v159
	v_and_b32_e32 v15, 0xffff0000, v159
	v_pk_mul_f32 v[8:9], v[8:9], v[14:15]
	s_nop 0
	v_cvt_pk_bf16_f32 v175, v8, v9
	s_waitcnt vmcnt(4)
	v_pk_mul_f32 v[12:13], v[20:21], v[0:1] op_sel_hi:[1,0]
	v_lshlrev_b32_e32 v14, 16, v160
	v_and_b32_e32 v15, 0xffff0000, v160
	v_pk_mul_f32 v[12:13], v[12:13], v[14:15]
	v_pk_mul_f32 v[8:9], v[22:23], v[0:1] op_sel_hi:[1,0]
	v_cvt_pk_bf16_f32 v176, v12, v13
	v_lshlrev_b32_e32 v14, 16, v161
	v_and_b32_e32 v15, 0xffff0000, v161
	v_pk_mul_f32 v[8:9], v[8:9], v[14:15]
	s_nop 0
	v_cvt_pk_bf16_f32 v177, v8, v9
	s_nop 1
	v_permlane32_swap_b32_e32 v174, v176
	v_permlane32_swap_b32_e32 v175, v177
	global_store_dwordx4 v[2:3], v[174:177], off offset:64
	s_waitcnt vmcnt(4)
	v_pk_mul_f32 v[12:13], v[24:25], v[0:1] op_sel_hi:[1,0]
	v_lshlrev_b32_e32 v14, 16, v162
	v_and_b32_e32 v15, 0xffff0000, v162
	v_pk_mul_f32 v[12:13], v[12:13], v[14:15]
	v_pk_mul_f32 v[8:9], v[26:27], v[0:1] op_sel_hi:[1,0]
	v_cvt_pk_bf16_f32 v178, v12, v13
	v_lshlrev_b32_e32 v14, 16, v163
	v_and_b32_e32 v15, 0xffff0000, v163
	v_pk_mul_f32 v[8:9], v[8:9], v[14:15]
	s_nop 0
	v_cvt_pk_bf16_f32 v179, v8, v9
	s_waitcnt vmcnt(3)
	v_pk_mul_f32 v[12:13], v[28:29], v[0:1] op_sel_hi:[1,0]
	v_lshlrev_b32_e32 v14, 16, v164
	v_and_b32_e32 v15, 0xffff0000, v164
	v_pk_mul_f32 v[12:13], v[12:13], v[14:15]
	v_pk_mul_f32 v[8:9], v[30:31], v[0:1] op_sel_hi:[1,0]
	v_cvt_pk_bf16_f32 v180, v12, v13
	v_lshlrev_b32_e32 v14, 16, v165
	v_and_b32_e32 v15, 0xffff0000, v165
	v_pk_mul_f32 v[8:9], v[8:9], v[14:15]
	s_nop 0
	v_cvt_pk_bf16_f32 v181, v8, v9
	s_nop 1
	v_permlane32_swap_b32_e32 v178, v180
	v_permlane32_swap_b32_e32 v179, v181
	global_store_dwordx4 v[2:3], v[178:181], off offset:96
